# attention V tile staged with conflict-free transposed LDS writes (wave = one 8-column chunk of 64 keys)
# baseline (speedup 1.0000x reference)
.LBB0_536:
	s_and_b64 vcc, exec, s[6:7]
	s_cbranch_vccz .LBB0_519
	s_ashr_i32 s53, s52, 5
	s_waitcnt vmcnt(14)
	v_mov_b32_e32 v2, v152
	s_sub_i32 s54, 15, s53
	s_lshl_b32 s71, s54, 8
	v_ashrrev_i32_e32 v0, 1, v2
	v_and_b32_e32 v102, 0xffffffe0, v0
	v_and_b32_e32 v116, 31, v2
	v_add_u32_e32 v103, s71, v102
	v_or_b32_e32 v104, v103, v116
	s_lshl_b32 s6, s52, 9
	s_and_b32 s14, s6, 0x3000
	v_ashrrev_i32_e32 v105, 31, v104
	v_lshl_add_u64 v[0:1], v[104:105], 0, s[14:15]
	s_waitcnt vmcnt(13)
	v_bfe_u32 v3, v2, 5, 1
	s_waitcnt vmcnt(11)
	v_lshlrev_b64 v[4:5], 6, v[0:1]
	s_waitcnt vmcnt(9)
	v_lshl_add_u64 v[6:7], s[24:25], 0, v[4:5]
	s_waitcnt vmcnt(8)
	v_lshlrev_b32_e32 v8, 5, v3
	s_waitcnt vmcnt(7)
	v_mov_b32_e32 v9, v101
	v_lshl_add_u64 v[4:5], s[26:27], 0, v[4:5]
	v_mov_b64_e32 v[20:21], s[42:43]
	s_waitcnt vmcnt(3)
	v_lshl_add_u64 v[12:13], v[6:7], 0, v[8:9]
	s_waitcnt vmcnt(0)
	v_lshl_add_u64 v[16:17], v[4:5], 0, v[8:9]
	s_and_b32 s72, s52, 7
	v_mad_u64_u32 v[20:21], s[6:7], v0, s66, v[20:21]
	global_load_dwordx4 v[4:7], v[16:17], off
	global_load_dwordx4 v[8:11], v[12:13], off
	s_nop 0
	global_load_dwordx4 v[12:15], v[12:13], off offset:16
	s_nop 0
	global_load_dwordx4 v[16:19], v[16:17], off offset:16
	v_mad_i32_i24 v21, v1, s66, v21
	s_mul_i32 s6, s72, 0xc0
	s_mov_b32 s7, s15
	v_lshl_add_u64 v[0:1], v[20:21], 0, s[6:7]
	v_lshlrev_b32_e32 v100, 4, v3
	v_lshl_add_u64 v[0:1], v[0:1], 0, v[100:101]
	global_load_dwordx4 v[20:23], v[0:1], off offset:128
	global_load_dwordx4 v[24:27], v[0:1], off offset:160
	global_load_dwordx4 v[64:67], v[0:1], off
	global_load_dwordx4 v[68:71], v[0:1], off offset:32
	global_load_dwordx4 v[72:75], v[0:1], off offset:64
	global_load_dwordx4 v[76:79], v[0:1], off offset:96
	s_lshl_b32 s10, s72, 8
	s_mov_b32 s11, s15
	v_cmp_gt_i32_e64 s[6:7], s67, v2
	s_waitcnt vmcnt(9)
	v_mov_b32_e32 v0, v4
	s_waitcnt vmcnt(8)
	v_mov_b32_e32 v1, v8
	v_mov_b32_e32 v28, v8
	v_mov_b32_e32 v29, v4
	v_mov_b32_e32 v8, v5
	s_waitcnt vmcnt(5)
	v_lshlrev_b32_e32 v39, 16, v20
	s_waitcnt vmcnt(4)
	v_lshlrev_b32_e32 v38, 16, v24
	v_mov_b32_e32 v30, v6
	v_mov_b32_e32 v31, v10
	v_mov_b32_e32 v32, v10
	v_mov_b32_e32 v33, v6
	v_mov_b32_e32 v10, v7
	v_mov_b32_e32 v6, v11
	v_mov_b32_e32 v34, v16
	v_mov_b32_e32 v35, v12
	v_mov_b32_e32 v36, v12
	v_mov_b32_e32 v12, v17
	v_and_b32_e32 v41, 0xffff0000, v20
	v_and_b32_e32 v40, 0xffff0000, v24
	v_lshlrev_b32_e32 v43, 16, v21
	v_lshlrev_b32_e32 v42, 16, v25
	v_and_b32_e32 v21, 0xffff0000, v21
	v_and_b32_e32 v20, 0xffff0000, v25
	v_lshlrev_b32_e32 v25, 16, v22
	v_lshlrev_b32_e32 v24, 16, v26
	v_and_b32_e32 v45, 0xffff0000, v22
	v_and_b32_e32 v44, 0xffff0000, v26
	v_pk_mul_f32 v[0:1], v[0:1], v[38:39]
	v_mov_b32_e32 v4, v9
	v_pk_mul_f32 v[28:29], v[28:29], v[38:39]
	v_pk_mul_f32 v[8:9], v[8:9], v[40:41]
	v_pk_mul_f32 v[10:11], v[10:11], v[20:21]
	v_pk_mul_f32 v[6:7], v[6:7], v[20:21]
	v_pk_mul_f32 v[20:21], v[34:35], v[24:25]
	v_pk_mul_f32 v[34:35], v[12:13], v[44:45]
	v_sub_f32_e32 v0, v1, v0
	v_mov_b32_e32 v37, v16
	v_pk_mul_f32 v[4:5], v[4:5], v[40:41]
	v_pk_mul_f32 v[30:31], v[30:31], v[42:43]
	v_pk_mul_f32 v[32:33], v[32:33], v[42:43]
	v_add_f32_e32 v1, v28, v29
	v_sub_f32_e32 v8, v9, v8
	v_cvt_pk_bf16_f32 v80, v0, v8
	v_sub_f32_e32 v0, v35, v34
	v_mov_b32_e32 v16, v13
	v_add_f32_e32 v4, v4, v5
	v_sub_f32_e32 v5, v31, v30
	v_add_f32_e32 v9, v32, v33
	v_sub_f32_e32 v10, v11, v10
	v_add_f32_e32 v6, v6, v7
	v_sub_f32_e32 v7, v21, v20
	v_cvt_pk_bf16_f32 v84, v1, v4
	v_cvt_pk_bf16_f32 v81, v5, v10
	v_cvt_pk_bf16_f32 v85, v9, v6
	v_cvt_pk_bf16_f32 v82, v7, v0
	v_pk_mul_f32 v[0:1], v[16:17], v[44:45]
	v_pk_mul_f32 v[24:25], v[36:37], v[24:25]
	v_add_f32_e32 v0, v0, v1
	v_add_f32_e32 v11, v24, v25
	v_cvt_pk_bf16_f32 v86, v11, v0
	v_lshlrev_b32_e32 v1, 16, v23
	v_lshlrev_b32_e32 v0, 16, v27
	v_mov_b32_e32 v4, v18
	v_mov_b32_e32 v5, v14
	v_pk_mul_f32 v[4:5], v[4:5], v[0:1]
	v_lshlrev_b32_e32 v10, 3, v2
	v_sub_f32_e32 v6, v5, v4
	v_mov_b32_e32 v4, v14
	v_mov_b32_e32 v5, v18
	v_pk_mul_f32 v[0:1], v[4:5], v[0:1]
	v_mov_b32_e32 v14, v19
	v_add_f32_e32 v7, v0, v1
	v_and_b32_e32 v1, 0xffff0000, v23
	v_and_b32_e32 v0, 0xffff0000, v27
	v_mov_b32_e32 v18, v15
	v_pk_mul_f32 v[4:5], v[14:15], v[0:1]
	v_pk_mul_f32 v[0:1], v[18:19], v[0:1]
	v_sub_f32_e32 v4, v5, v4
	v_add_f32_e32 v0, v0, v1
	v_cvt_pk_bf16_f32 v83, v6, v4
	v_cvt_pk_bf16_f32 v87, v7, v0
	v_ashrrev_i32_e32 v0, 3, v2
	v_ashrrev_i32_e32 v1, 31, v0
	v_lshl_add_u64 v[4:5], v[0:1], 0, s[14:15]
	v_lshlrev_b64 v[4:5], 11, v[4:5]
	v_lshl_add_u64 v[4:5], s[44:45], 0, v[4:5]
	v_lshl_add_u64 v[6:7], v[4:5], 0, s[10:11]
	v_and_b32_e32 v5, 56, v10
	v_lshlrev_b32_e32 v8, 1, v5
	v_mov_b32_e32 v9, v101
	v_lshl_add_u64 v[6:7], v[6:7], 0, v[8:9]
	global_load_dwordx4 v[88:91], v[6:7], off
	v_and_b32_e32 v160, 63, v2
	v_mov_b32_e32 v161, 0
	v_lshrrev_b32_e32 v162, 6, v2
	v_mov_b32_e32 v163, 0
	v_lshl_add_u64 v[166:167], v[160:161], 0, s[14:15]
	v_lshlrev_b64 v[166:167], 11, v[166:167]
	v_mul_u32_u24_e32 v159, 0x480, v162
	v_lshlrev_b32_e32 v162, 4, v162
	v_lshl_add_u64 v[164:165], s[44:45], 0, v[166:167]
	v_lshl_add_u64 v[164:165], v[164:165], 0, s[10:11]
	v_lshl_add_u64 v[164:165], v[164:165], 0, v[162:163]
	v_lshl_add_u32 v158, v160, 1, v159
	v_lshlrev_b64 v[166:167], 11, v[160:161]
	global_load_dwordx4 v[92:95], v[164:165], off offset:128
	v_bfe_u32 v4, v2, 2, 6
	v_and_b32_e32 v6, 24, v10
	s_and_saveexec_b64 s[8:9], s[6:7]
	s_cbranch_execz .LBB0_539
	v_or_b32_e32 v7, s14, v4
	v_lshlrev_b32_e32 v8, 6, v7
	v_mov_b32_e32 v9, v101
	v_lshl_add_u64 v[8:9], s[46:47], 0, v[8:9]
	v_lshlrev_b32_e32 v10, 1, v6
	v_mov_b32_e32 v11, v101
	v_lshl_add_u64 v[8:9], v[8:9], 0, v[10:11]
	global_load_dwordx4 v[96:99], v[8:9], off
.LBB0_539:
	s_or_b64 exec, exec, s[8:9]
	v_mul_lo_u32 v7, v0, s65
	v_add_lshl_u32 v118, v7, v5, 1
	v_mad_u32_u24 v6, v4, s65, v6
	v_mad_u32_u24 v5, v5, s68, v0
	v_lshl_add_u32 v119, v6, 1, v114
	v_add_u32_e32 v6, 0, v118
	v_lshl_add_u32 v120, v5, 1, 0
	s_waitcnt vmcnt(1)
	ds_write_b128 v6, v[88:91]
	s_waitcnt vmcnt(0)
	ds_write_b16 v158, v92 offset:26624
	ds_write_b16_d16_hi v158, v92 offset:26768
	ds_write_b16 v158, v93 offset:26912
	ds_write_b16_d16_hi v158, v93 offset:27056
	ds_write_b16 v158, v94 offset:27200
	ds_write_b16_d16_hi v158, v94 offset:27344
	ds_write_b16 v158, v95 offset:27488
	ds_write_b16_d16_hi v158, v95 offset:27632
	s_and_saveexec_b64 s[8:9], s[6:7]
	v_add_u32_e32 v5, 0, v119
	ds_write_b128 v5, v[96:99]
	s_or_b64 exec, exec, s[8:9]
	v_lshlrev_b32_e32 v5, 3, v3
	v_lshlrev_b32_e32 v117, 2, v3
	v_cmp_eq_u32_e64 s[8:9], 0, v3
	v_mul_u32_u24_e32 v3, 0x90, v116
	s_bfe_u32 s11, s52, 0x20003
	v_add3_u32 v125, 0, v5, v3
	v_and_b32_e32 v3, 3, v2
	v_lshlrev_b32_e32 v4, 6, v4
	s_lshl_b32 s40, s11, 23
	s_mov_b32 s41, s15
	v_lshlrev_b64 v[0:1], 11, v[0:1]
	v_and_b32_e32 v2, 7, v2
	v_mul_u32_u24_e32 v6, 0x68, v116
	v_lshl_or_b32 v4, s11, 18, v4
	v_lshl_add_u64 v[0:1], s[40:41], 0, v[0:1]
	v_lshlrev_b32_e32 v2, 4, v2
	v_add_lshl_u32 v123, v5, v6, 1
	v_lshl_or_b32 v4, v3, 4, v4
	v_mov_b32_e32 v5, v101
	v_or3_b32 v0, v0, s10, v2
	v_mov_b32_e32 v14, v101
	v_mov_b32_e32 v15, v101
	v_lshl_add_u32 v105, v102, 2, 0
	s_lshl_b32 s73, s54, 2
	v_lshl_add_u64 v[106:107], s[28:29], 0, v[4:5]
	v_lshl_add_u64 v[108:109], s[30:31], 0, v[0:1]
	v_lshl_add_u64 v[156:157], s[40:41], 0, v[166:167]
	v_or3_b32 v156, v156, s10, v162
	v_lshl_add_u64 v[156:157], s[30:31], 0, v[156:157]
	s_lshl_b32 s10, s53, 2
	v_mov_b32_e32 v0, v101
	v_mov_b32_e32 v1, v101
	v_mov_b32_e32 v2, v101
	v_mov_b32_e32 v3, v101
	v_mov_b32_e32 v4, v101
	v_mov_b32_e32 v6, v101
	v_mov_b32_e32 v7, v101
	v_mov_b32_e32 v8, v101
	v_mov_b32_e32 v9, v101
	v_mov_b32_e32 v10, v101
	v_mov_b32_e32 v11, v101
	v_mov_b32_e32 v12, v101
	v_mov_b32_e32 v13, v101
	v_mov_b64_e32 v[30:31], v[14:15]
	s_add_i32 s73, s73, 4
	v_or_b32_e32 v122, 31, v103
	v_lshl_add_u32 v121, v116, 2, v105
	s_mov_b32 s74, 1
	v_add_u32_e32 v124, 0x1a00, v123
	s_sub_i32 s75, s10, 64
	v_mov_b32_e32 v132, 0xf149f2ca
	v_mov_b32_e32 v126, 0
	s_mov_b32 s76, 63
	v_mov_b64_e32 v[28:29], v[12:13]
	v_mov_b64_e32 v[26:27], v[10:11]
	v_mov_b64_e32 v[24:25], v[8:9]
	v_mov_b64_e32 v[22:23], v[6:7]
	v_mov_b64_e32 v[20:21], v[4:5]
	v_mov_b64_e32 v[18:19], v[2:3]
	v_mov_b64_e32 v[16:17], v[0:1]
	s_waitcnt lgkmcnt(0)
	s_barrier
	s_branch .LBB0_544

.LBB0_543:
	s_add_i32 s74, s74, 1
	s_add_i32 s76, s76, 64
	s_add_i32 s10, s75, s74
	v_lshl_add_u64 v[106:107], v[106:107], 0, s[48:49]
	s_cmp_eq_u32 s10, 1
	v_lshl_add_u64 v[108:109], v[108:109], 0, s[50:51]
	v_lshl_add_u64 v[156:157], v[156:157], 0, s[50:51]
	s_waitcnt lgkmcnt(0)
	s_barrier
	s_cbranch_scc1 .LBB0_559
.LBB0_544:
	s_cmp_lt_u32 s74, s73
	s_cselect_b64 s[52:53], -1, 0
	s_cmp_ge_u32 s74, s73
	s_cbranch_scc1 .LBB0_548
	global_load_dwordx4 v[88:91], v[108:109], off
	global_load_dwordx4 v[92:95], v[156:157], off offset:128
	s_and_saveexec_b64 s[10:11], s[6:7]
	s_cbranch_execz .LBB0_547
	global_load_dwordx4 v[96:99], v[106:107], off

.LBB0_556:
	s_or_b64 exec, exec, s[54:55]
	s_andn2_b64 vcc, exec, s[52:53]
	s_cbranch_vccnz .LBB0_543
	s_xor_b32 s10, s77, 1
	s_mul_i32 s11, s10, 0x3400
	s_add_i32 s33, s11, 0
	v_add_u32_e32 v32, s33, v118
	s_mulk_i32 s10, 0x2400
	s_waitcnt vmcnt(1)
	ds_write_b128 v32, v[88:91]
	v_add_u32_e32 v32, s10, v158
	s_waitcnt vmcnt(0)
	ds_write_b16 v32, v92 offset:26624
	ds_write_b16_d16_hi v32, v92 offset:26768
	ds_write_b16 v32, v93 offset:26912
	ds_write_b16_d16_hi v32, v93 offset:27056
	ds_write_b16 v32, v94 offset:27200
	ds_write_b16_d16_hi v32, v94 offset:27344
	ds_write_b16 v32, v95 offset:27488
	ds_write_b16_d16_hi v32, v95 offset:27632
	s_and_saveexec_b64 s[10:11], s[6:7]
	s_cbranch_execz .LBB0_542
	v_add_u32_e32 v32, s33, v119
	ds_write_b128 v32, v[96:99]
	s_branch .LBB0_542
